# v37 + conflict-free hyena B/x LDS table layout (row base 4160*j+32*(j>>2))
# baseline (speedup 1.0000x reference)
.LBB0_792:
	s_or_b64 exec, exec, s[6:7]
	s_waitcnt vmcnt(0)
	v_or_b32_e32 v191, v39, v52
	v_and_b32_e32 v39, 0xff0, v36
	s_add_i32 s2, 0, 0x10200
	s_add_i32 s13, 0, 0x18400
	v_or_b32_e32 v196, v43, v42
	v_add_u32_e32 v145, s2, v39
	v_add_u32_e32 v163, s13, v39
	v_bfe_u32 v39, v144, 3, 1
	v_mul_u32_u24_e32 v43, 0x204, v46
	v_or_b32_e32 v195, v37, v47
	v_bfe_u32 v37, v144, 4, 2
	v_lshrrev_b32_e32 v44, 2, v144
	v_or_b32_e32 v43, v43, v39
	v_cmp_eq_u32_e64 s[6:7], 0, v39
	v_and_b32_e32 v39, 8, v144
	v_and_b32_e32 v44, 0xf0, v44
	v_sub_u32_e32 v45, v43, v37
	v_mov_b32_e32 v47, 0x800
	v_cmp_ne_u32_e64 s[8:9], 0, v39
	s_movk_i32 s12, 0x1040
	v_add_u32_e32 v44, v45, v44
	v_mov_b32_e32 v45, 0x1800
	v_cndmask_b32_e64 v164, v47, 0, s[8:9]
	v_mov_b32_e32 v47, s2
	v_or_b32_e32 v190, v41, v40
	v_lshrrev_b32_e32 v40, 6, v144
	v_lshrrev_b32_e32 v41, 8, v144
	v_lshl_add_u32 v44, v44, 4, v45
	v_lshlrev_b32_e32 v45, 4, v37
	v_mad_u32_u24 v165, v46, s12, v47
	v_lshrrev_b32_e32 v250, 2, v46
	v_lshl_add_u32 v165, v250, 5, v165
	v_lshlrev_b32_e32 v47, 3, v37
	v_mov_b32_e32 v37, s13
	v_mov_b32_e32 v129, 0
	v_mul_u32_u24_e32 v160, 0x1040, v41
	v_add_u32_e32 v41, 0x200, v144
	v_add_lshl_u32 v39, v40, v39, 8
	v_mad_u32_u24 v167, v46, s12, v37
	v_lshl_add_u32 v167, v250, 5, v167
	v_mov_b32_e32 v37, v129
	v_or_b32_e32 v194, v131, v48
	v_lshrrev_b32_e32 v41, 8, v41
	v_or_b32_e32 v134, v39, v47
	v_add_u32_e32 v48, v165, v39
	v_mov_b32_e32 v39, v129
	v_lshl_add_u64 v[138:139], s[16:17], 0, v[36:37]
	v_lshlrev_b32_e32 v37, 4, v43
	v_mul_u32_u24_e32 v161, 0x1040, v41
	v_add_u32_e32 v41, 0x600, v144
	v_lshl_add_u64 v[136:137], s[18:19], 0, v[38:39]
	v_lshlrev_b32_e32 v38, 12, v46
	v_lshl_add_u32 v37, v40, 8, v37
	v_lshrrev_b32_e32 v41, 8, v41
	v_lshl_add_u64 v[38:39], s[22:23], 0, v[38:39]
	v_mov_b32_e32 v135, v129
	v_sub_u32_e32 v37, v37, v45
	v_mul_u32_u24_e32 v162, 0x1040, v41
	v_add_u32_e32 v162, 32, v162
	v_sub_u32_e32 v41, 0x1ff0, v36
	v_sub_u32_e32 v42, 0x2000, v36
	v_lshl_add_u64 v[38:39], v[38:39], 0, v[134:135]
	s_mov_b64 s[12:13], 0x12a00000
	v_add_u32_e32 v37, 0, v37
	v_add_u32_e32 v175, 0, v36
	s_add_i32 s2, 0, 0x20600
	v_or_b32_e32 v189, v54, v53
	v_or_b32_e32 v192, v133, v51
	v_or_b32_e32 v193, v50, v49
	s_mov_b32 s15, 0
	v_add_u32_e32 v166, v165, v45
	v_or_b32_e32 v168, 32, v134
	v_or_b32_e32 v169, 64, v134
	v_or_b32_e32 v170, 0x60, v134
	v_or_b32_e32 v171, 0x80, v134
	v_or_b32_e32 v172, 0xa0, v134
	v_or_b32_e32 v173, 0xc0, v134
	v_or_b32_e32 v174, 0xe0, v134
	v_lshl_add_u64 v[140:141], v[38:39], 0, s[12:13]
	v_add_u32_e32 v135, 0x1700, v37
	v_add_u32_e32 v176, 0x20600, v175
	s_waitcnt lgkmcnt(0)
	s_add_i32 s46, 0, 0x22600
	v_mov_b32_e32 v177, 0x3000
	v_mov_b32_e32 v178, 0x6000
	v_mov_b32_e32 v179, 0x1000
	v_mov_b32_e32 v180, 0x4000
	v_mov_b32_e32 v181, 0x7000
	s_mov_b32 s47, 0x1000706
	s_mov_b64 s[16:17], 0x4000000
	v_add_u32_e32 v182, v48, v47
	v_mov_b32_e32 v183, 0x2000
	v_mov_b32_e32 v184, 0x5000
	v_mov_b32_e32 v185, 0x8000
	s_mov_b64 s[18:19], 0x1c00000
	v_mov_b32_e32 v200, v129
	v_mov_b32_e32 v201, v129
	v_mov_b32_e32 v202, v129
	v_mov_b32_e32 v203, v129
	v_add_u32_e32 v186, s2, v41
	v_add_u32_e32 v187, s2, v42
	v_add_u32_e32 v188, 0, v44
	s_branch .LBB0_794

.LBB0_794:
	ds_write_b128 v176, v[0:3]
	s_and_saveexec_b64 s[28:29], s[4:5]
	v_mov_b32_e32 v36, s46
	ds_write_b128 v36, v[200:203]
	s_or_b64 exec, exec, s[28:29]
	s_add_i32 s34, s15, s14
	v_readlane_b32 s56, v248, 8
	s_ashr_i32 s35, s34, 31
	v_readlane_b32 s57, v248, 9
	s_lshl_b64 s[42:43], s[34:35], 2
	v_readlane_b32 s58, v248, 10
	v_readlane_b32 s59, v248, 11
	s_mov_b64 s[48:49], s[56:57]
	s_add_u32 s36, s48, s42
	s_mov_b64 s[50:51], s[58:59]
	s_addc_u32 s37, s49, s43
	s_add_u32 s40, s50, s42
	global_load_dword v38, v177, s[36:37]
	global_load_dword v40, v129, s[36:37]
	global_load_dword v36, v178, s[36:37]
	s_addc_u32 s41, s51, s43
	global_load_dword v42, v129, s[40:41]
	v_and_b32_e32 v46, 0xffff0000, v5
	v_and_b32_e32 v48, 0xffff0000, v4
	v_and_b32_e32 v66, 0xffff0000, v9
	v_and_b32_e32 v45, 16, v7
	v_and_b32_e32 v44, 0xffff0000, v6
	v_and_b32_e32 v47, 16, v6
	v_lshlrev_b32_e32 v57, 16, v6
	v_and_b32_e32 v49, 16, v5
	v_lshlrev_b32_e32 v59, 16, v5
	v_lshlrev_b32_e32 v61, 16, v4
	v_lshlrev_b32_e32 v60, 16, v195
	v_and_b32_e32 v51, 16, v11
	v_and_b32_e32 v50, 0xffff0000, v10
	v_lshlrev_b32_e32 v69, 16, v10
	v_mov_b32_e32 v56, v46
	v_mov_b32_e32 v58, v48
	v_mov_b32_e32 v68, v66
	v_mov_b32_e32 v52, v44
	v_pk_mov_b32 v[76:77], v[60:61], v[48:49] op_sel:[1,0]
	v_mov_b32_e32 v62, v50
	v_pk_mov_b32 v[80:81], v[58:59], v[46:47] op_sel:[1,0]
	v_pk_mov_b32 v[82:83], v[56:57], v[44:45] op_sel:[1,0]
	v_pk_mov_b32 v[86:87], v[68:69], v[50:51] op_sel:[1,0]
	global_load_dword v48, v180, s[36:37]
	global_load_dword v44, v181, s[36:37]
	global_load_dword v50, v179, s[36:37]
	global_load_dword v46, v179, s[40:41]
	v_lshlrev_b32_e32 v53, 16, v7
	v_and_b32_e32 v55, 0xffff0000, v195
	v_and_b32_e32 v54, 0xffff0000, v7
	v_and_b32_e32 v70, 0xffff0000, v8
	v_and_b32_e32 v67, 16, v10
	v_and_b32_e32 v71, 16, v9
	v_lshlrev_b32_e32 v73, 16, v9
	v_lshlrev_b32_e32 v75, 16, v8
	v_lshlrev_b32_e32 v74, 16, v194
	v_mov_b32_e32 v72, v70
	v_pk_mov_b32 v[78:79], v[52:53], v[54:55] op_sel:[1,0]
	v_pk_mov_b32 v[70:71], v[74:75], v[70:71] op_sel:[1,0]
	v_pk_mov_b32 v[66:67], v[72:73], v[66:67] op_sel:[1,0]
	v_add_u32_e32 v37, v145, v160
	v_lshlrev_b32_e32 v63, 16, v11
	v_and_b32_e32 v65, 0xffff0000, v194
	v_and_b32_e32 v64, 0xffff0000, v11
	v_pk_mov_b32 v[84:85], v[62:63], v[64:65] op_sel:[1,0]
	v_add_u32_e32 v142, v163, v160
	v_add_u32_e32 v148, v163, v161
	v_add_u32_e32 v199, v163, v162
	s_lshl_b64 s[30:31], s[34:35], 15
	v_mov_b32_e32 v147, 0
	v_mov_b32_e32 v153, 0
	v_readlane_b32 s60, v248, 12
	v_readlane_b32 s61, v248, 13
	v_readlane_b32 s62, v248, 14
	v_readlane_b32 s63, v248, 15
	v_readlane_b32 s64, v248, 16
	v_readlane_b32 s65, v248, 17
	v_readlane_b32 s66, v248, 18
	v_readlane_b32 s67, v248, 19
	v_readlane_b32 s68, v248, 20
	v_readlane_b32 s69, v248, 21
	v_readlane_b32 s70, v248, 22
	v_readlane_b32 s71, v248, 23
	s_waitcnt vmcnt(7)
	v_pk_mul_f32 v[76:77], v[38:39], v[76:77] op_sel_hi:[0,1]
	v_pk_mul_f32 v[80:81], v[38:39], v[80:81] op_sel_hi:[0,1]
	v_pk_mul_f32 v[82:83], v[38:39], v[82:83] op_sel_hi:[0,1]
	v_pk_mul_f32 v[78:79], v[38:39], v[78:79] op_sel_hi:[0,1]
	v_pk_mul_f32 v[70:71], v[38:39], v[70:71] op_sel_hi:[0,1]
	v_pk_mul_f32 v[66:67], v[38:39], v[66:67] op_sel_hi:[0,1]
	s_waitcnt vmcnt(6)
	v_pk_fma_f32 v[60:61], v[40:41], v[60:61], v[76:77] op_sel_hi:[0,1,1]
	v_pk_fma_f32 v[76:77], v[40:41], v[58:59], v[80:81] op_sel_hi:[0,1,1]
	v_pk_fma_f32 v[80:81], v[40:41], v[56:57], v[82:83] op_sel_hi:[0,1,1]
	v_pk_fma_f32 v[78:79], v[40:41], v[52:53], v[78:79] op_sel_hi:[0,1,1]
	v_pk_mul_f32 v[86:87], v[38:39], v[86:87] op_sel_hi:[0,1]
	v_pk_fma_f32 v[70:71], v[40:41], v[74:75], v[70:71] op_sel_hi:[0,1,1]
	v_pk_fma_f32 v[66:67], v[40:41], v[72:73], v[66:67] op_sel_hi:[0,1,1]
	s_waitcnt vmcnt(5)
	v_pk_fma_f32 v[58:59], v[36:37], v[58:59], v[60:61] op_sel_hi:[0,1,1]
	v_pk_fma_f32 v[56:57], v[36:37], v[56:57], v[76:77] op_sel_hi:[0,1,1]
	v_pk_fma_f32 v[52:53], v[36:37], v[52:53], v[80:81] op_sel_hi:[0,1,1]
	v_pk_fma_f32 v[54:55], v[36:37], v[54:55], v[78:79] op_sel_hi:[0,1,1]
	v_pk_mul_f32 v[84:85], v[38:39], v[84:85] op_sel_hi:[0,1]
	v_pk_fma_f32 v[74:75], v[40:41], v[68:69], v[86:87] op_sel_hi:[0,1,1]
	v_pk_fma_f32 v[60:61], v[36:37], v[72:73], v[70:71] op_sel_hi:[0,1,1]
	v_pk_fma_f32 v[66:67], v[36:37], v[68:69], v[66:67] op_sel_hi:[0,1,1]
	s_waitcnt vmcnt(4)
	v_pk_add_f32 v[58:59], v[42:43], v[58:59] op_sel_hi:[0,1]
	v_pk_add_f32 v[56:57], v[42:43], v[56:57] op_sel_hi:[0,1]
	v_pk_add_f32 v[68:69], v[42:43], v[52:53] op_sel_hi:[0,1]
	v_pk_add_f32 v[70:71], v[42:43], v[54:55] op_sel_hi:[0,1]
	v_pk_fma_f32 v[82:83], v[40:41], v[62:63], v[84:85] op_sel_hi:[0,1,1]
	v_cvt_pk_bf16_f32 v52, v58, v59
	v_cvt_pk_bf16_f32 v53, v56, v57
	v_cvt_pk_bf16_f32 v54, v68, v69
	v_cvt_pk_bf16_f32 v55, v70, v71
	v_pk_fma_f32 v[62:63], v[36:37], v[62:63], v[74:75] op_sel_hi:[0,1,1]
	ds_write_b128 v37, v[52:55]
	v_pk_fma_f32 v[52:53], v[36:37], v[64:65], v[82:83] op_sel_hi:[0,1,1]
	v_pk_add_f32 v[60:61], v[42:43], v[60:61] op_sel_hi:[0,1]
	v_pk_add_f32 v[66:67], v[42:43], v[66:67] op_sel_hi:[0,1]
	v_pk_add_f32 v[62:63], v[42:43], v[62:63] op_sel_hi:[0,1]
	v_pk_add_f32 v[56:57], v[42:43], v[52:53] op_sel_hi:[0,1]
	v_cvt_pk_bf16_f32 v52, v60, v61
	v_cvt_pk_bf16_f32 v53, v66, v67
	v_cvt_pk_bf16_f32 v54, v62, v63
	v_cvt_pk_bf16_f32 v55, v56, v57
	v_add_u32_e32 v39, v145, v161
	v_and_b32_e32 v60, 0xffff0000, v13
	ds_write_b128 v39, v[52:55]
	v_and_b32_e32 v53, 16, v15
	v_and_b32_e32 v52, 0xffff0000, v14
	v_lshlrev_b32_e32 v63, 16, v14
	v_mov_b32_e32 v62, v60
	v_and_b32_e32 v64, 0xffff0000, v12
	v_mov_b32_e32 v54, v52
	v_and_b32_e32 v61, 16, v14
	v_lshlrev_b32_e32 v67, 16, v13
	v_mov_b32_e32 v66, v64
	v_pk_mov_b32 v[52:53], v[62:63], v[52:53] op_sel:[1,0]
	v_pk_mov_b32 v[60:61], v[66:67], v[60:61] op_sel:[1,0]
	v_pk_mul_f32 v[52:53], v[38:39], v[52:53] op_sel_hi:[0,1]
	v_lshlrev_b32_e32 v55, 16, v15
	v_and_b32_e32 v57, 0xffff0000, v193
	v_and_b32_e32 v56, 0xffff0000, v15
	v_and_b32_e32 v65, 16, v13
	v_lshlrev_b32_e32 v69, 16, v12
	v_lshlrev_b32_e32 v68, 16, v193
	v_pk_mul_f32 v[60:61], v[38:39], v[60:61] op_sel_hi:[0,1]
	v_pk_fma_f32 v[52:53], v[40:41], v[62:63], v[52:53] op_sel_hi:[0,1,1]
	v_pk_mov_b32 v[58:59], v[54:55], v[56:57] op_sel:[1,0]
	v_pk_mov_b32 v[64:65], v[68:69], v[64:65] op_sel:[1,0]
	v_pk_fma_f32 v[60:61], v[40:41], v[66:67], v[60:61] op_sel_hi:[0,1,1]
	v_pk_fma_f32 v[52:53], v[36:37], v[54:55], v[52:53] op_sel_hi:[0,1,1]
	v_pk_mul_f32 v[64:65], v[38:39], v[64:65] op_sel_hi:[0,1]
	v_pk_fma_f32 v[60:61], v[36:37], v[62:63], v[60:61] op_sel_hi:[0,1,1]
	v_pk_add_f32 v[62:63], v[42:43], v[52:53] op_sel_hi:[0,1]
	v_pk_mul_f32 v[52:53], v[38:39], v[58:59] op_sel_hi:[0,1]
	v_pk_fma_f32 v[64:65], v[40:41], v[68:69], v[64:65] op_sel_hi:[0,1,1]
	v_pk_fma_f32 v[52:53], v[40:41], v[54:55], v[52:53] op_sel_hi:[0,1,1]
	v_pk_fma_f32 v[64:65], v[36:37], v[66:67], v[64:65] op_sel_hi:[0,1,1]
	v_pk_fma_f32 v[52:53], v[36:37], v[56:57], v[52:53] op_sel_hi:[0,1,1]
	v_pk_add_f32 v[64:65], v[42:43], v[64:65] op_sel_hi:[0,1]
	v_pk_add_f32 v[60:61], v[42:43], v[60:61] op_sel_hi:[0,1]
	v_pk_add_f32 v[56:57], v[42:43], v[52:53] op_sel_hi:[0,1]
	v_cvt_pk_bf16_f32 v52, v64, v65
	v_cvt_pk_bf16_f32 v53, v60, v61
	v_cvt_pk_bf16_f32 v54, v62, v63
	v_cvt_pk_bf16_f32 v55, v56, v57
	ds_write_b128 v37, v[52:55] offset:16672
	v_and_b32_e32 v52, 0xffff0000, v18
	v_and_b32_e32 v60, 0xffff0000, v17
	v_and_b32_e32 v64, 0xffff0000, v16
	v_and_b32_e32 v53, 16, v19
	v_lshlrev_b32_e32 v55, 16, v19
	v_mov_b32_e32 v54, v52
	v_and_b32_e32 v57, 0xffff0000, v192
	v_and_b32_e32 v56, 0xffff0000, v19
	v_and_b32_e32 v61, 16, v18
	v_lshlrev_b32_e32 v63, 16, v18
	v_mov_b32_e32 v62, v60
	v_and_b32_e32 v65, 16, v17
	v_lshlrev_b32_e32 v67, 16, v17
	v_mov_b32_e32 v66, v64
	v_lshlrev_b32_e32 v69, 16, v16
	v_lshlrev_b32_e32 v68, 16, v192
	v_pk_mov_b32 v[58:59], v[54:55], v[56:57] op_sel:[1,0]
	v_pk_mov_b32 v[64:65], v[68:69], v[64:65] op_sel:[1,0]
	v_pk_mov_b32 v[60:61], v[66:67], v[60:61] op_sel:[1,0]
	v_pk_mov_b32 v[52:53], v[62:63], v[52:53] op_sel:[1,0]
	v_pk_mul_f32 v[64:65], v[38:39], v[64:65] op_sel_hi:[0,1]
	v_pk_mul_f32 v[60:61], v[38:39], v[60:61] op_sel_hi:[0,1]
	v_pk_mul_f32 v[52:53], v[38:39], v[52:53] op_sel_hi:[0,1]
	v_pk_mul_f32 v[38:39], v[38:39], v[58:59] op_sel_hi:[0,1]
	v_pk_fma_f32 v[64:65], v[40:41], v[68:69], v[64:65] op_sel_hi:[0,1,1]
	v_pk_fma_f32 v[60:61], v[40:41], v[66:67], v[60:61] op_sel_hi:[0,1,1]
	v_pk_fma_f32 v[52:53], v[40:41], v[62:63], v[52:53] op_sel_hi:[0,1,1]
	v_pk_fma_f32 v[38:39], v[40:41], v[54:55], v[38:39] op_sel_hi:[0,1,1]
	v_pk_fma_f32 v[64:65], v[36:37], v[66:67], v[64:65] op_sel_hi:[0,1,1]
	v_pk_fma_f32 v[60:61], v[36:37], v[62:63], v[60:61] op_sel_hi:[0,1,1]
	v_pk_fma_f32 v[52:53], v[36:37], v[54:55], v[52:53] op_sel_hi:[0,1,1]
	v_pk_fma_f32 v[36:37], v[36:37], v[56:57], v[38:39] op_sel_hi:[0,1,1]
	v_pk_add_f32 v[64:65], v[42:43], v[64:65] op_sel_hi:[0,1]
	v_pk_add_f32 v[60:61], v[42:43], v[60:61] op_sel_hi:[0,1]
	v_pk_add_f32 v[52:53], v[42:43], v[52:53] op_sel_hi:[0,1]
	v_pk_add_f32 v[40:41], v[42:43], v[36:37] op_sel_hi:[0,1]
	v_cvt_pk_bf16_f32 v36, v64, v65
	v_cvt_pk_bf16_f32 v37, v60, v61
	v_cvt_pk_bf16_f32 v38, v52, v53
	v_cvt_pk_bf16_f32 v39, v40, v41
	v_add_u32_e32 v40, v145, v162
	v_and_b32_e32 v52, 0xffff0000, v21
	ds_write_b128 v40, v[36:39]
	v_and_b32_e32 v37, 16, v23
	v_and_b32_e32 v36, 0xffff0000, v22
	v_lshlrev_b32_e32 v55, 16, v22
	v_mov_b32_e32 v54, v52
	v_and_b32_e32 v56, 0xffff0000, v20
	v_mov_b32_e32 v38, v36
	v_and_b32_e32 v53, 16, v22
	v_lshlrev_b32_e32 v59, 16, v21
	v_mov_b32_e32 v58, v56
	v_pk_mov_b32 v[36:37], v[54:55], v[36:37] op_sel:[1,0]
	v_pk_mov_b32 v[52:53], v[58:59], v[52:53] op_sel:[1,0]
	s_waitcnt vmcnt(3)
	v_pk_mul_f32 v[36:37], v[48:49], v[36:37] op_sel_hi:[0,1]
	v_lshlrev_b32_e32 v39, 16, v23
	v_and_b32_e32 v41, 0xffff0000, v191
	v_and_b32_e32 v40, 0xffff0000, v23
	v_and_b32_e32 v57, 16, v21
	v_lshlrev_b32_e32 v61, 16, v20
	v_lshlrev_b32_e32 v60, 16, v191
	v_pk_mul_f32 v[52:53], v[48:49], v[52:53] op_sel_hi:[0,1]
	s_waitcnt vmcnt(1)
	v_pk_fma_f32 v[36:37], v[50:51], v[54:55], v[36:37] op_sel_hi:[0,1,1]
	v_pk_mov_b32 v[42:43], v[38:39], v[40:41] op_sel:[1,0]
	v_pk_mov_b32 v[56:57], v[60:61], v[56:57] op_sel:[1,0]
	v_pk_fma_f32 v[52:53], v[50:51], v[58:59], v[52:53] op_sel_hi:[0,1,1]
	v_pk_fma_f32 v[36:37], v[44:45], v[38:39], v[36:37] op_sel_hi:[0,1,1]
	v_pk_mul_f32 v[56:57], v[48:49], v[56:57] op_sel_hi:[0,1]
	v_pk_fma_f32 v[52:53], v[44:45], v[54:55], v[52:53] op_sel_hi:[0,1,1]
	s_waitcnt vmcnt(0)
	v_pk_add_f32 v[54:55], v[46:47], v[36:37] op_sel_hi:[0,1]
	v_pk_mul_f32 v[36:37], v[48:49], v[42:43] op_sel_hi:[0,1]
	v_pk_fma_f32 v[56:57], v[50:51], v[60:61], v[56:57] op_sel_hi:[0,1,1]
	v_pk_fma_f32 v[36:37], v[50:51], v[38:39], v[36:37] op_sel_hi:[0,1,1]
	v_pk_fma_f32 v[56:57], v[44:45], v[58:59], v[56:57] op_sel_hi:[0,1,1]
	v_pk_fma_f32 v[36:37], v[44:45], v[40:41], v[36:37] op_sel_hi:[0,1,1]
	v_pk_add_f32 v[56:57], v[46:47], v[56:57] op_sel_hi:[0,1]
	v_pk_add_f32 v[52:53], v[46:47], v[52:53] op_sel_hi:[0,1]
	v_pk_add_f32 v[40:41], v[46:47], v[36:37] op_sel_hi:[0,1]
	v_cvt_pk_bf16_f32 v36, v56, v57
	v_cvt_pk_bf16_f32 v37, v52, v53
	v_cvt_pk_bf16_f32 v38, v54, v55
	v_cvt_pk_bf16_f32 v39, v40, v41
	v_and_b32_e32 v52, 0xffff0000, v25
	ds_write_b128 v142, v[36:39]
	v_and_b32_e32 v37, 16, v27
	v_and_b32_e32 v36, 0xffff0000, v26
	v_lshlrev_b32_e32 v55, 16, v26
	v_mov_b32_e32 v54, v52
	v_and_b32_e32 v56, 0xffff0000, v24
	v_mov_b32_e32 v38, v36
	v_and_b32_e32 v53, 16, v26
	v_lshlrev_b32_e32 v59, 16, v25
	v_mov_b32_e32 v58, v56
	v_pk_mov_b32 v[36:37], v[54:55], v[36:37] op_sel:[1,0]
	v_pk_mov_b32 v[52:53], v[58:59], v[52:53] op_sel:[1,0]
	v_pk_mul_f32 v[36:37], v[48:49], v[36:37] op_sel_hi:[0,1]
	v_lshlrev_b32_e32 v39, 16, v27
	v_and_b32_e32 v41, 0xffff0000, v190
	v_and_b32_e32 v40, 0xffff0000, v27
	v_and_b32_e32 v57, 16, v25
	v_lshlrev_b32_e32 v61, 16, v24
	v_lshlrev_b32_e32 v60, 16, v190
	v_pk_mul_f32 v[52:53], v[48:49], v[52:53] op_sel_hi:[0,1]
	v_pk_fma_f32 v[36:37], v[50:51], v[54:55], v[36:37] op_sel_hi:[0,1,1]
	v_pk_mov_b32 v[42:43], v[38:39], v[40:41] op_sel:[1,0]
	v_pk_mov_b32 v[56:57], v[60:61], v[56:57] op_sel:[1,0]
	v_pk_fma_f32 v[52:53], v[50:51], v[58:59], v[52:53] op_sel_hi:[0,1,1]
	v_pk_fma_f32 v[36:37], v[44:45], v[38:39], v[36:37] op_sel_hi:[0,1,1]
	v_pk_mul_f32 v[56:57], v[48:49], v[56:57] op_sel_hi:[0,1]
	v_pk_fma_f32 v[52:53], v[44:45], v[54:55], v[52:53] op_sel_hi:[0,1,1]
	v_pk_add_f32 v[54:55], v[46:47], v[36:37] op_sel_hi:[0,1]
	v_pk_mul_f32 v[36:37], v[48:49], v[42:43] op_sel_hi:[0,1]
	v_pk_fma_f32 v[56:57], v[50:51], v[60:61], v[56:57] op_sel_hi:[0,1,1]
	v_pk_fma_f32 v[36:37], v[50:51], v[38:39], v[36:37] op_sel_hi:[0,1,1]
	v_pk_fma_f32 v[56:57], v[44:45], v[58:59], v[56:57] op_sel_hi:[0,1,1]
	v_pk_fma_f32 v[36:37], v[44:45], v[40:41], v[36:37] op_sel_hi:[0,1,1]
	v_pk_add_f32 v[56:57], v[46:47], v[56:57] op_sel_hi:[0,1]
	v_pk_add_f32 v[52:53], v[46:47], v[52:53] op_sel_hi:[0,1]
	v_pk_add_f32 v[40:41], v[46:47], v[36:37] op_sel_hi:[0,1]
	v_cvt_pk_bf16_f32 v36, v56, v57
	v_cvt_pk_bf16_f32 v37, v52, v53
	v_cvt_pk_bf16_f32 v38, v54, v55
	v_cvt_pk_bf16_f32 v39, v40, v41
	v_and_b32_e32 v52, 0xffff0000, v29
	ds_write_b128 v148, v[36:39]
	v_and_b32_e32 v37, 16, v31
	v_and_b32_e32 v36, 0xffff0000, v30
	v_lshlrev_b32_e32 v55, 16, v30
	v_mov_b32_e32 v54, v52
	v_and_b32_e32 v56, 0xffff0000, v28
	v_mov_b32_e32 v38, v36
	v_and_b32_e32 v53, 16, v30
	v_lshlrev_b32_e32 v59, 16, v29
	v_mov_b32_e32 v58, v56
	v_pk_mov_b32 v[36:37], v[54:55], v[36:37] op_sel:[1,0]
	v_pk_mov_b32 v[52:53], v[58:59], v[52:53] op_sel:[1,0]
	v_pk_mul_f32 v[36:37], v[48:49], v[36:37] op_sel_hi:[0,1]
	v_lshlrev_b32_e32 v39, 16, v31
	v_and_b32_e32 v41, 0xffff0000, v189
	v_and_b32_e32 v40, 0xffff0000, v31
	v_and_b32_e32 v57, 16, v29
	v_lshlrev_b32_e32 v61, 16, v28
	v_lshlrev_b32_e32 v60, 16, v189
	v_pk_mul_f32 v[52:53], v[48:49], v[52:53] op_sel_hi:[0,1]
	v_pk_fma_f32 v[36:37], v[50:51], v[54:55], v[36:37] op_sel_hi:[0,1,1]
	v_pk_mov_b32 v[42:43], v[38:39], v[40:41] op_sel:[1,0]
	v_pk_mov_b32 v[56:57], v[60:61], v[56:57] op_sel:[1,0]
	v_pk_fma_f32 v[52:53], v[50:51], v[58:59], v[52:53] op_sel_hi:[0,1,1]
	v_pk_fma_f32 v[36:37], v[44:45], v[38:39], v[36:37] op_sel_hi:[0,1,1]
	v_pk_mul_f32 v[56:57], v[48:49], v[56:57] op_sel_hi:[0,1]
	v_pk_fma_f32 v[52:53], v[44:45], v[54:55], v[52:53] op_sel_hi:[0,1,1]
	v_pk_add_f32 v[54:55], v[46:47], v[36:37] op_sel_hi:[0,1]
	v_pk_mul_f32 v[36:37], v[48:49], v[42:43] op_sel_hi:[0,1]
	v_pk_fma_f32 v[56:57], v[50:51], v[60:61], v[56:57] op_sel_hi:[0,1,1]
	v_pk_fma_f32 v[36:37], v[50:51], v[38:39], v[36:37] op_sel_hi:[0,1,1]
	v_pk_fma_f32 v[56:57], v[44:45], v[58:59], v[56:57] op_sel_hi:[0,1,1]
	v_pk_fma_f32 v[36:37], v[44:45], v[40:41], v[36:37] op_sel_hi:[0,1,1]
	v_pk_add_f32 v[56:57], v[46:47], v[56:57] op_sel_hi:[0,1]
	v_pk_add_f32 v[52:53], v[46:47], v[52:53] op_sel_hi:[0,1]
	v_pk_add_f32 v[40:41], v[46:47], v[36:37] op_sel_hi:[0,1]
	v_cvt_pk_bf16_f32 v36, v56, v57
	v_cvt_pk_bf16_f32 v37, v52, v53
	v_cvt_pk_bf16_f32 v38, v54, v55
	v_cvt_pk_bf16_f32 v39, v40, v41
	v_and_b32_e32 v52, 0xffff0000, v33
	ds_write_b128 v142, v[36:39] offset:16672
	v_and_b32_e32 v37, 16, v35
	v_and_b32_e32 v36, 0xffff0000, v34
	v_lshlrev_b32_e32 v55, 16, v34
	v_mov_b32_e32 v54, v52
	v_and_b32_e32 v56, 0xffff0000, v32
	v_mov_b32_e32 v38, v36
	v_and_b32_e32 v53, 16, v34
	v_lshlrev_b32_e32 v59, 16, v33
	v_mov_b32_e32 v58, v56
	v_pk_mov_b32 v[36:37], v[54:55], v[36:37] op_sel:[1,0]
	v_pk_mov_b32 v[52:53], v[58:59], v[52:53] op_sel:[1,0]
	v_pk_mul_f32 v[36:37], v[48:49], v[36:37] op_sel_hi:[0,1]
	v_lshlrev_b32_e32 v39, 16, v35
	v_and_b32_e32 v41, 0xffff0000, v196
	v_and_b32_e32 v40, 0xffff0000, v35
	v_and_b32_e32 v57, 16, v33
	v_lshlrev_b32_e32 v61, 16, v32
	v_lshlrev_b32_e32 v60, 16, v196
	v_pk_mul_f32 v[52:53], v[48:49], v[52:53] op_sel_hi:[0,1]
	v_pk_fma_f32 v[36:37], v[50:51], v[54:55], v[36:37] op_sel_hi:[0,1,1]
	v_pk_mov_b32 v[42:43], v[38:39], v[40:41] op_sel:[1,0]
	v_pk_mov_b32 v[56:57], v[60:61], v[56:57] op_sel:[1,0]
	v_pk_fma_f32 v[52:53], v[50:51], v[58:59], v[52:53] op_sel_hi:[0,1,1]
	v_pk_fma_f32 v[36:37], v[44:45], v[38:39], v[36:37] op_sel_hi:[0,1,1]
	v_pk_mul_f32 v[56:57], v[48:49], v[56:57] op_sel_hi:[0,1]
	v_pk_fma_f32 v[52:53], v[44:45], v[54:55], v[52:53] op_sel_hi:[0,1,1]
	v_pk_add_f32 v[54:55], v[46:47], v[36:37] op_sel_hi:[0,1]
	v_pk_mul_f32 v[36:37], v[48:49], v[42:43] op_sel_hi:[0,1]
	v_pk_fma_f32 v[56:57], v[50:51], v[60:61], v[56:57] op_sel_hi:[0,1,1]
	v_pk_fma_f32 v[36:37], v[50:51], v[38:39], v[36:37] op_sel_hi:[0,1,1]
	v_pk_fma_f32 v[56:57], v[44:45], v[58:59], v[56:57] op_sel_hi:[0,1,1]
	v_pk_fma_f32 v[36:37], v[44:45], v[40:41], v[36:37] op_sel_hi:[0,1,1]
	v_pk_add_f32 v[56:57], v[46:47], v[56:57] op_sel_hi:[0,1]
	v_pk_add_f32 v[52:53], v[46:47], v[52:53] op_sel_hi:[0,1]
	v_pk_add_f32 v[40:41], v[46:47], v[36:37] op_sel_hi:[0,1]
	v_cvt_pk_bf16_f32 v36, v56, v57
	v_cvt_pk_bf16_f32 v37, v52, v53
	v_cvt_pk_bf16_f32 v38, v54, v55
	v_cvt_pk_bf16_f32 v39, v40, v41
	ds_write_b128 v199, v[36:39]
	s_waitcnt lgkmcnt(0)
	s_barrier
	ds_read_b128 v[36:39], v187
	ds_read_b128 v[40:43], v186
	s_waitcnt lgkmcnt(1)
	v_pk_mov_b32 v[50:51], v[36:37], v[38:39] op_sel:[1,0]
	s_waitcnt lgkmcnt(0)
	v_pk_mov_b32 v[48:49], v[42:43], v[36:37] op_sel:[1,0]
	v_perm_b32 v44, v43, v36, s47
	v_perm_b32 v45, v36, v37, s47
	ds_write_b128 v175, v[48:51] offset:16512
	v_perm_b32 v50, v42, v43, s47
	ds_write_b128 v175, v[36:39]
	v_perm_b32 v46, v37, v38, s47
	v_perm_b32 v47, v38, v39, s47
	v_mov_b32_e32 v54, v36
	v_mov_b32_e32 v55, v37
	v_perm_b32 v36, v41, v42, s47
	v_mov_b32_e32 v37, v50
	v_mov_b32_e32 v38, v44
	v_mov_b32_e32 v39, v45
	ds_write_b128 v175, v[36:39] offset:41280
	v_mov_b32_e32 v39, v36
	v_lshl_add_u64 v[36:37], v[136:137], 0, s[30:31]
	ds_write_b128 v175, v[44:47] offset:8256
	v_mov_b32_e32 v51, v44
	v_mov_b32_e32 v52, v45
	v_mov_b32_e32 v53, v46
	v_pk_mov_b32 v[46:47], v[40:41], v[42:43] op_sel:[1,0]
	v_perm_b32 v38, v40, v41, s47
	v_mov_b32_e32 v40, v50
	v_mov_b32_e32 v41, v44
	v_lshl_add_u64 v[36:37], v[36:37], 0, s[16:17]
	ds_write_b128 v175, v[50:53] offset:24768
	v_mov_b32_e32 v52, v42
	v_mov_b32_e32 v53, v43
	ds_write_b128 v175, v[38:41] offset:57792
	v_lshl_add_u64 v[38:39], v[36:37], 0, v[128:129]
	ds_write_b128 v175, v[52:55] offset:33024
	ds_write_b128 v175, v[46:49] offset:49536
	s_waitcnt lgkmcnt(0)
	s_barrier
	global_load_dwordx4 v[48:51], v[38:39], off nt
	s_and_saveexec_b64 s[28:29], s[0:1]
	s_cbranch_execz .LBB0_798
	global_load_short_d16_hi v153, v[38:39], off offset:-2

.LBB0_818:
	s_waitcnt vmcnt(0)
	s_add_u32 s42, s38, s42
	s_addc_u32 s43, s39, s43
	s_waitcnt lgkmcnt(0)
	global_load_dword v60, v129, s[42:43]
	v_add_u32_e32 v122, v167, v134
	v_add_u32_e32 v121, v165, v134
	ds_read2_b64 v[62:65], v122 offset1:4
	ds_read2_b64 v[66:69], v121 offset1:4
	ds_read2_b64 v[70:73], v122 offset0:8 offset1:12
	ds_read2_b64 v[74:77], v121 offset0:8 offset1:12
	ds_read2_b64 v[84:87], v122 offset0:16 offset1:20
	ds_read2_b64 v[88:91], v121 offset0:16 offset1:20
	global_load_dword v120, v179, s[42:43]
	s_waitcnt lgkmcnt(4)
	v_lshlrev_b32_e32 v104, 16, v66
	v_and_b32_e32 v105, 0xffff0000, v66
	v_lshlrev_b32_e32 v66, 16, v67
	v_and_b32_e32 v67, 0xffff0000, v67
	v_lshlrev_b32_e32 v78, 16, v62
	v_and_b32_e32 v79, 0xffff0000, v62
	v_lshlrev_b32_e32 v62, 16, v63
	v_and_b32_e32 v63, 0xffff0000, v63
	s_waitcnt lgkmcnt(2)
	v_lshlrev_b32_e32 v204, 16, v74
	v_and_b32_e32 v205, 0xffff0000, v74
	v_lshlrev_b32_e32 v74, 16, v75
	v_and_b32_e32 v75, 0xffff0000, v75
	v_lshlrev_b32_e32 v208, 16, v76
	v_and_b32_e32 v209, 0xffff0000, v76
	v_lshlrev_b32_e32 v124, 16, v68
	v_and_b32_e32 v125, 0xffff0000, v68
	v_lshlrev_b32_e32 v68, 16, v69
	v_and_b32_e32 v69, 0xffff0000, v69
	v_lshlrev_b32_e32 v126, 16, v70
	v_and_b32_e32 v127, 0xffff0000, v70
	v_lshlrev_b32_e32 v70, 16, v71
	v_and_b32_e32 v71, 0xffff0000, v71
	v_lshlrev_b32_e32 v206, 16, v72
	v_and_b32_e32 v207, 0xffff0000, v72
	s_waitcnt lgkmcnt(0)
	v_lshlrev_b32_e32 v216, 16, v90
	v_and_b32_e32 v217, 0xffff0000, v90
	v_lshlrev_b32_e32 v106, 16, v64
	v_and_b32_e32 v107, 0xffff0000, v64
	v_lshlrev_b32_e32 v64, 16, v65
	v_and_b32_e32 v65, 0xffff0000, v65
	v_lshlrev_b32_e32 v76, 16, v77
	v_and_b32_e32 v77, 0xffff0000, v77
	v_lshlrev_b32_e32 v212, 16, v88
	v_and_b32_e32 v213, 0xffff0000, v88
	v_lshlrev_b32_e32 v88, 16, v89
	v_and_b32_e32 v89, 0xffff0000, v89
	v_lshlrev_b32_e32 v214, 16, v86
	v_and_b32_e32 v215, 0xffff0000, v86
	v_lshlrev_b32_e32 v72, 16, v73
	v_and_b32_e32 v73, 0xffff0000, v73
	v_lshlrev_b32_e32 v210, 16, v84
	v_and_b32_e32 v211, 0xffff0000, v84
	v_lshlrev_b32_e32 v84, 16, v85
	v_and_b32_e32 v85, 0xffff0000, v85
	s_waitcnt vmcnt(1)
	v_pk_fma_f32 v[104:105], v[60:61], v[104:105], v[116:117] op_sel_hi:[0,1,1]
	v_pk_fma_f32 v[66:67], v[60:61], v[66:67], v[118:119] op_sel_hi:[0,1,1]
	v_pk_fma_f32 v[74:75], v[60:61], v[74:75], v[98:99] op_sel_hi:[0,1,1]
	v_pk_fma_f32 v[98:99], v[60:61], v[208:209], v[108:109] op_sel_hi:[0,1,1]
	v_pk_mul_f32 v[78:79], v[104:105], v[78:79]
	v_pk_mul_f32 v[62:63], v[66:67], v[62:63]
	v_pk_fma_f32 v[100:101], v[60:61], v[124:125], v[100:101] op_sel_hi:[0,1,1]
	v_pk_fma_f32 v[68:69], v[60:61], v[68:69], v[102:103] op_sel_hi:[0,1,1]
	v_pk_fma_f32 v[96:97], v[60:61], v[204:205], v[96:97] op_sel_hi:[0,1,1]
	v_pk_mul_f32 v[70:71], v[74:75], v[70:71]
	v_pk_mul_f32 v[74:75], v[98:99], v[206:207]
	v_cvt_pk_bf16_f32 v78, v78, v79
	v_cvt_pk_bf16_f32 v79, v62, v63
	v_pk_fma_f32 v[62:63], v[60:61], v[216:217], v[92:93] op_sel_hi:[0,1,1]
	v_pk_fma_f32 v[76:77], v[60:61], v[76:77], v[110:111] op_sel_hi:[0,1,1]
	v_pk_fma_f32 v[102:103], v[60:61], v[212:213], v[112:113] op_sel_hi:[0,1,1]
	v_pk_fma_f32 v[88:89], v[60:61], v[88:89], v[114:115] op_sel_hi:[0,1,1]
	v_pk_mul_f32 v[66:67], v[100:101], v[106:107]
	v_pk_mul_f32 v[64:65], v[68:69], v[64:65]
	v_pk_mul_f32 v[68:69], v[96:97], v[126:127]
	v_cvt_pk_bf16_f32 v97, v70, v71
	v_cvt_pk_bf16_f32 v70, v74, v75
	v_pk_mul_f32 v[74:75], v[62:63], v[214:215]
	v_lshlrev_b32_e32 v62, 16, v91
	v_and_b32_e32 v63, 0xffff0000, v91
	v_pk_mul_f32 v[72:73], v[76:77], v[72:73]
	v_pk_mul_f32 v[76:77], v[102:103], v[210:211]
	v_pk_mul_f32 v[84:85], v[88:89], v[84:85]
	v_cvt_pk_bf16_f32 v88, v66, v67
	v_cvt_pk_bf16_f32 v96, v68, v69
	v_lshlrev_b32_e32 v66, 16, v87
	v_and_b32_e32 v67, 0xffff0000, v87
	v_pk_fma_f32 v[68:69], v[60:61], v[62:63], v[94:95] op_sel_hi:[0,1,1]
	v_cvt_pk_bf16_f32 v71, v72, v73
	v_cvt_pk_bf16_f32 v72, v76, v77
	v_pk_mul_f32 v[76:77], v[68:69], v[66:67]
	ds_read2_b64 v[66:69], v121 offset0:24 offset1:28
	v_cvt_pk_bf16_f32 v89, v64, v65
	ds_read2_b64 v[62:65], v122 offset0:24 offset1:28
	v_cvt_pk_bf16_f32 v73, v84, v85
	v_cvt_pk_bf16_f32 v74, v74, v75
	s_waitcnt lgkmcnt(1)
	v_lshlrev_b32_e32 v84, 16, v66
	v_and_b32_e32 v85, 0xffff0000, v66
	v_cvt_pk_bf16_f32 v75, v76, v77
	s_waitcnt lgkmcnt(0)
	v_lshlrev_b32_e32 v76, 16, v62
	v_and_b32_e32 v77, 0xffff0000, v62
	v_pk_fma_f32 v[80:81], v[60:61], v[84:85], v[80:81] op_sel_hi:[0,1,1]
	v_lshlrev_b32_e32 v66, 16, v67
	v_and_b32_e32 v67, 0xffff0000, v67
	v_pk_mul_f32 v[76:77], v[80:81], v[76:77]
	v_lshlrev_b32_e32 v62, 16, v63
	v_and_b32_e32 v63, 0xffff0000, v63
	v_pk_fma_f32 v[66:67], v[60:61], v[66:67], v[82:83] op_sel_hi:[0,1,1]
	v_pk_mul_f32 v[62:63], v[66:67], v[62:63]
	v_cvt_pk_bf16_f32 v66, v76, v77
	v_lshlrev_b32_e32 v76, 16, v68
	v_and_b32_e32 v77, 0xffff0000, v68
	v_cvt_pk_bf16_f32 v67, v62, v63
	v_lshlrev_b32_e32 v62, 16, v64
	v_and_b32_e32 v63, 0xffff0000, v64
	v_pk_fma_f32 v[56:57], v[60:61], v[76:77], v[56:57] op_sel_hi:[0,1,1]
	v_pk_mul_f32 v[56:57], v[56:57], v[62:63]
	v_lshlrev_b32_e32 v62, 16, v65
	v_and_b32_e32 v63, 0xffff0000, v65
	v_lshlrev_b32_e32 v64, 16, v69
	v_and_b32_e32 v65, 0xffff0000, v69
	v_pk_fma_f32 v[58:59], v[60:61], v[64:65], v[58:59] op_sel_hi:[0,1,1]
	v_pk_mul_f32 v[58:59], v[58:59], v[62:63]
	v_cvt_pk_bf16_f32 v56, v56, v57
	v_cvt_pk_bf16_f32 v57, v58, v59
	s_barrier
	ds_write2_b64 v182, v[78:79], v[88:89] offset1:4
	ds_write2_b64 v182, v[96:97], v[70:71] offset0:8 offset1:12
	ds_write2_b64 v182, v[72:73], v[74:75] offset0:16 offset1:20
	ds_write2_b64 v182, v[66:67], v[56:57] offset0:24 offset1:28
	ds_write_b128 v176, v[52:55]
	s_and_saveexec_b64 s[28:29], s[4:5]
	v_mov_b32_e32 v52, s46
	ds_write_b128 v52, v[200:203]
	s_or_b64 exec, exec, s[28:29]
	global_load_dword v57, v183, s[36:37]
	global_load_dword v56, v184, s[36:37]
	global_load_dword v54, v185, s[36:37]
	global_load_dword v52, v183, s[40:41]
	v_and_b32_e32 v64, 0xffff0000, v49
	v_lshlrev_b32_e32 v58, 16, v48
	v_and_b32_e32 v61, 0xffff0000, v51
	v_and_b32_e32 v63, 16, v51
	v_and_b32_e32 v62, 0xffff0000, v50
	v_lshlrev_b32_e32 v51, 16, v51
	v_and_b32_e32 v65, 16, v50
	v_lshlrev_b32_e32 v67, 16, v50
	v_and_b32_e32 v48, 0xffff0000, v48
	v_lshlrev_b32_e32 v49, 16, v49
	v_and_b32_e32 v74, 0xffff0000, v45
	v_mov_b32_e32 v66, v64
	v_lshlrev_b32_e32 v68, 16, v44
	v_and_b32_e32 v71, 0xffff0000, v47
	v_and_b32_e32 v73, 16, v47
	v_and_b32_e32 v72, 0xffff0000, v46
	v_lshlrev_b32_e32 v47, 16, v47
	v_and_b32_e32 v75, 16, v46
	v_lshlrev_b32_e32 v77, 16, v46
	v_and_b32_e32 v44, 0xffff0000, v44
	v_lshlrev_b32_e32 v45, 16, v45
	v_mov_b32_e32 v50, v62
	v_mov_b32_e32 v60, v51
	v_mov_b32_e32 v152, v48
	v_pk_mov_b32 v[64:65], v[48:49], v[64:65] op_sel:[1,0]
	v_mov_b32_e32 v76, v74
	v_pk_mov_b32 v[62:63], v[66:67], v[62:63] op_sel:[1,0]
	v_and_b32_e32 v59, 0xffff0000, v43
	v_mov_b32_e32 v146, v61
	v_mov_b32_e32 v46, v72
	v_mov_b32_e32 v70, v47
	v_mov_b32_e32 v158, v44
	v_pk_mov_b32 v[74:75], v[44:45], v[74:75] op_sel:[1,0]
	v_pk_mov_b32 v[72:73], v[76:77], v[72:73] op_sel:[1,0]
	v_lshlrev_b32_e32 v69, 16, v43
	v_mov_b32_e32 v154, v71
	v_lshlrev_b32_e32 v78, 16, v40
	v_and_b32_e32 v40, 0xffff0000, v40
	v_mov_b32_e32 v156, v40
	v_and_b32_e32 v81, 16, v43
	v_and_b32_e32 v80, 0xffff0000, v42
	v_lshlrev_b32_e32 v43, 16, v42
	v_mov_b32_e32 v150, v59
	s_add_i32 s15, s15, 1
	s_add_i32 s2, s34, 0x81
	s_cmp_lt_u32 s15, s54
	s_cselect_b32 s34, s2, 0x100000
	s_cmpk_gt_i32 s34, 0x47f
	s_waitcnt vmcnt(3)
	v_mov_b32_e32 v84, v57
	s_waitcnt vmcnt(2)
	v_pk_mul_f32 v[82:83], v[152:153], v[56:57]
	v_pk_mul_f32 v[64:65], v[56:57], v[64:65] op_sel_hi:[0,1]
	v_pk_mul_f32 v[62:63], v[56:57], v[62:63] op_sel_hi:[0,1]
	v_pk_mul_f32 v[60:61], v[56:57], v[60:61] op_sel_hi:[0,1]
	v_pk_mul_f32 v[86:87], v[158:159], v[56:57]
	v_pk_mul_f32 v[74:75], v[56:57], v[74:75] op_sel_hi:[0,1]
	v_pk_mul_f32 v[72:73], v[56:57], v[72:73] op_sel_hi:[0,1]
	v_pk_mul_f32 v[70:71], v[56:57], v[70:71] op_sel_hi:[0,1]
	v_pk_fma_f32 v[82:83], v[56:57], v[58:59], v[82:83] op_sel:[0,0,1] op_sel_hi:[1,0,0]
	v_pk_fma_f32 v[64:65], v[84:85], v[48:49], v[64:65] op_sel_hi:[0,1,1]
	v_pk_fma_f32 v[62:63], v[84:85], v[66:67], v[62:63] op_sel_hi:[0,1,1]
	v_pk_fma_f32 v[60:61], v[84:85], v[50:51], v[60:61] op_sel_hi:[0,1,1]
	v_pk_fma_f32 v[86:87], v[56:57], v[68:69], v[86:87] op_sel:[0,0,1] op_sel_hi:[1,0,0]
	v_pk_fma_f32 v[74:75], v[84:85], v[44:45], v[74:75] op_sel_hi:[0,1,1]
	v_pk_fma_f32 v[72:73], v[84:85], v[76:77], v[72:73] op_sel_hi:[0,1,1]
	v_pk_fma_f32 v[70:71], v[84:85], v[46:47], v[70:71] op_sel_hi:[0,1,1]
	s_waitcnt vmcnt(1)
	v_pk_fma_f32 v[48:49], v[54:55], v[48:49], v[82:83] op_sel_hi:[0,1,1]
	v_pk_fma_f32 v[64:65], v[54:55], v[66:67], v[64:65] op_sel_hi:[0,1,1]
	v_pk_fma_f32 v[50:51], v[54:55], v[50:51], v[62:63] op_sel_hi:[0,1,1]
	v_pk_fma_f32 v[60:61], v[54:55], v[146:147], v[60:61] op_sel_hi:[0,1,1]
	v_pk_fma_f32 v[44:45], v[54:55], v[44:45], v[86:87] op_sel_hi:[0,1,1]
	v_pk_fma_f32 v[62:63], v[54:55], v[76:77], v[74:75] op_sel_hi:[0,1,1]
	v_pk_fma_f32 v[46:47], v[54:55], v[46:47], v[72:73] op_sel_hi:[0,1,1]
	v_pk_fma_f32 v[66:67], v[54:55], v[154:155], v[70:71] op_sel_hi:[0,1,1]
	s_waitcnt vmcnt(0)
	v_pk_add_f32 v[48:49], v[52:53], v[48:49] op_sel_hi:[0,1]
	v_pk_add_f32 v[64:65], v[52:53], v[64:65] op_sel_hi:[0,1]
	v_pk_add_f32 v[50:51], v[52:53], v[50:51] op_sel_hi:[0,1]
	v_pk_add_f32 v[60:61], v[52:53], v[60:61] op_sel_hi:[0,1]
	v_pk_add_f32 v[70:71], v[52:53], v[44:45] op_sel_hi:[0,1]
	v_pk_add_f32 v[62:63], v[52:53], v[62:63] op_sel_hi:[0,1]
	v_pk_add_f32 v[72:73], v[52:53], v[46:47] op_sel_hi:[0,1]
	v_pk_add_f32 v[66:67], v[52:53], v[66:67] op_sel_hi:[0,1]
	v_cvt_pk_bf16_f32 v44, v48, v49
	v_cvt_pk_bf16_f32 v45, v64, v65
	v_cvt_pk_bf16_f32 v46, v50, v51
	v_cvt_pk_bf16_f32 v47, v60, v61
	v_cvt_pk_bf16_f32 v48, v70, v71
	v_cvt_pk_bf16_f32 v49, v62, v63
	v_cvt_pk_bf16_f32 v50, v72, v73
	v_cvt_pk_bf16_f32 v51, v66, v67
	ds_write_b128 v142, v[44:47]
	ds_write_b128 v148, v[48:51]
	v_and_b32_e32 v45, 16, v42
	v_and_b32_e32 v44, 0xffff0000, v41
	v_lshlrev_b32_e32 v41, 16, v41
	v_mov_b32_e32 v42, v44
	v_pk_mul_f32 v[46:47], v[156:157], v[56:57]
	v_pk_mov_b32 v[44:45], v[40:41], v[44:45] op_sel:[1,0]
	v_pk_fma_f32 v[46:47], v[56:57], v[78:79], v[46:47] op_sel:[0,0,1] op_sel_hi:[1,0,0]
	v_pk_mul_f32 v[44:45], v[56:57], v[44:45] op_sel_hi:[0,1]
	v_pk_fma_f32 v[46:47], v[54:55], v[40:41], v[46:47] op_sel_hi:[0,1,1]
	v_pk_fma_f32 v[40:41], v[84:85], v[40:41], v[44:45] op_sel_hi:[0,1,1]
	v_pk_fma_f32 v[40:41], v[54:55], v[42:43], v[40:41] op_sel_hi:[0,1,1]
	v_pk_add_f32 v[44:45], v[52:53], v[40:41] op_sel_hi:[0,1]
	v_pk_mov_b32 v[40:41], v[42:43], v[80:81] op_sel:[1,0]
	v_mov_b32_e32 v68, v80
	v_pk_mul_f32 v[40:41], v[56:57], v[40:41] op_sel_hi:[0,1]
	v_pk_fma_f32 v[40:41], v[84:85], v[42:43], v[40:41] op_sel_hi:[0,1,1]
	v_mov_b32_e32 v58, v69
	v_pk_fma_f32 v[40:41], v[54:55], v[68:69], v[40:41] op_sel_hi:[0,1,1]
	v_pk_add_f32 v[42:43], v[52:53], v[40:41] op_sel_hi:[0,1]
	v_pk_mul_f32 v[40:41], v[56:57], v[58:59] op_sel_hi:[0,1]
	v_pk_fma_f32 v[40:41], v[84:85], v[68:69], v[40:41] op_sel_hi:[0,1,1]
	v_pk_fma_f32 v[40:41], v[54:55], v[150:151], v[40:41] op_sel_hi:[0,1,1]
	v_pk_add_f32 v[46:47], v[52:53], v[46:47] op_sel_hi:[0,1]
	v_pk_add_f32 v[48:49], v[52:53], v[40:41] op_sel_hi:[0,1]
	v_cvt_pk_bf16_f32 v40, v46, v47
	v_cvt_pk_bf16_f32 v41, v44, v45
	v_cvt_pk_bf16_f32 v42, v42, v43
	v_cvt_pk_bf16_f32 v43, v48, v49
	ds_write_b128 v142, v[40:43] offset:16672
	v_lshlrev_b32_e32 v40, 16, v36
	v_and_b32_e32 v36, 0xffff0000, v36
	v_and_b32_e32 v49, 16, v38
	v_and_b32_e32 v48, 0xffff0000, v37
	v_lshlrev_b32_e32 v37, 16, v37
	v_mov_b32_e32 v148, v36
	v_and_b32_e32 v43, 0xffff0000, v39
	v_and_b32_e32 v45, 16, v39
	v_and_b32_e32 v44, 0xffff0000, v38
	v_lshlrev_b32_e32 v47, 16, v39
	v_lshlrev_b32_e32 v39, 16, v38
	v_mov_b32_e32 v38, v48
	v_pk_mul_f32 v[50:51], v[148:149], v[56:57]
	v_pk_mov_b32 v[48:49], v[36:37], v[48:49] op_sel:[1,0]
	v_pk_fma_f32 v[40:41], v[56:57], v[40:41], v[50:51] op_sel:[0,0,1] op_sel_hi:[1,0,0]
	v_pk_mul_f32 v[48:49], v[56:57], v[48:49] op_sel_hi:[0,1]
	v_pk_fma_f32 v[40:41], v[54:55], v[36:37], v[40:41] op_sel_hi:[0,1,1]
	v_pk_fma_f32 v[36:37], v[84:85], v[36:37], v[48:49] op_sel_hi:[0,1,1]
	v_pk_fma_f32 v[36:37], v[54:55], v[38:39], v[36:37] op_sel_hi:[0,1,1]
	v_pk_add_f32 v[48:49], v[52:53], v[36:37] op_sel_hi:[0,1]
	v_pk_mov_b32 v[36:37], v[38:39], v[44:45] op_sel:[1,0]
	v_mov_b32_e32 v46, v44
	v_pk_mul_f32 v[36:37], v[56:57], v[36:37] op_sel_hi:[0,1]
	v_pk_fma_f32 v[36:37], v[84:85], v[38:39], v[36:37] op_sel_hi:[0,1,1]
	v_mov_b32_e32 v42, v47
	v_pk_fma_f32 v[36:37], v[54:55], v[46:47], v[36:37] op_sel_hi:[0,1,1]
	v_pk_add_f32 v[38:39], v[52:53], v[36:37] op_sel_hi:[0,1]
	v_pk_mul_f32 v[36:37], v[56:57], v[42:43] op_sel_hi:[0,1]
	v_pk_fma_f32 v[36:37], v[84:85], v[46:47], v[36:37] op_sel_hi:[0,1,1]
	v_mov_b32_e32 v142, v43
	v_pk_fma_f32 v[36:37], v[54:55], v[142:143], v[36:37] op_sel_hi:[0,1,1]
	v_pk_add_f32 v[40:41], v[52:53], v[40:41] op_sel_hi:[0,1]
	v_pk_add_f32 v[42:43], v[52:53], v[36:37] op_sel_hi:[0,1]
	v_cvt_pk_bf16_f32 v36, v40, v41
	v_cvt_pk_bf16_f32 v37, v48, v49
	v_cvt_pk_bf16_f32 v38, v38, v39
	v_cvt_pk_bf16_f32 v39, v42, v43
	ds_write_b128 v199, v[36:39]
	s_waitcnt lgkmcnt(0)
	s_barrier
	ds_read_b128 v[36:39], v186
	ds_read_b128 v[40:43], v187
	s_waitcnt lgkmcnt(0)
	v_perm_b32 v44, v39, v40, s47
	v_perm_b32 v45, v40, v41, s47
	v_perm_b32 v46, v41, v42, s47
	v_pk_mov_b32 v[48:49], v[38:39], v[40:41] op_sel:[1,0]
	v_pk_mov_b32 v[50:51], v[40:41], v[42:43] op_sel:[1,0]
	ds_write_b128 v175, v[40:43]
	v_perm_b32 v47, v42, v43, s47
	ds_write_b128 v175, v[48:51] offset:16512
	v_perm_b32 v50, v38, v39, s47
	v_mov_b32_e32 v51, v44
	v_mov_b32_e32 v52, v45
	v_mov_b32_e32 v53, v46
	v_mov_b32_e32 v54, v40
	v_perm_b32 v40, v37, v38, s47
	ds_write_b128 v175, v[44:47] offset:8256
	ds_write_b128 v175, v[50:53] offset:24768
	v_mov_b32_e32 v52, v38
	v_mov_b32_e32 v53, v39
	v_mov_b32_e32 v55, v41
	v_mov_b32_e32 v41, v50
	v_mov_b32_e32 v42, v44
	v_mov_b32_e32 v43, v45
	v_pk_mov_b32 v[46:47], v[36:37], v[38:39] op_sel:[1,0]
	v_perm_b32 v36, v36, v37, s47
	v_mov_b32_e32 v37, v40
	v_mov_b32_e32 v38, v50
	v_mov_b32_e32 v39, v44
	ds_write_b128 v175, v[52:55] offset:33024
	ds_write_b128 v175, v[40:43] offset:41280
	ds_write_b128 v175, v[46:49] offset:49536
	ds_write_b128 v175, v[36:39] offset:57792
	s_waitcnt lgkmcnt(0)
	s_barrier
	s_cbranch_scc1 .LBB0_854
	s_add_i32 s12, s34, 0xffffff80
	s_ashr_i32 s13, s12, 31
	s_lshl_b64 s[28:29], s[12:13], 13
	s_lshl_b64 s[12:13], s[12:13], 15
	v_lshl_add_u64 v[0:1], v[138:139], 0, s[28:29]
	v_lshl_add_u64 v[16:17], v[136:137], 0, s[12:13]
	v_lshl_add_u64 v[18:19], v[16:17], 0, v[128:129]
	global_load_dwordx4 v[0:3], v[0:1], off
	s_nop 0
	global_load_dwordx4 v[4:7], v[18:19], off nt
	v_mov_b32_e32 v226, 0
	v_mov_b32_e32 v218, 0
	s_and_saveexec_b64 s[28:29], s[0:1]
	s_cbranch_execz .LBB0_823
	global_load_ushort v218, v[18:19], off offset:-2

	.amdhsa_kernel _Z4mega6Params
		.amdhsa_group_segment_fixed_size 0
		.amdhsa_private_segment_fixed_size 0
		.amdhsa_kernarg_size 568
		.amdhsa_user_sgpr_count 2
		.amdhsa_user_sgpr_dispatch_ptr 0
		.amdhsa_user_sgpr_queue_ptr 0
		.amdhsa_user_sgpr_kernarg_segment_ptr 1
		.amdhsa_user_sgpr_dispatch_id 0
		.amdhsa_user_sgpr_kernarg_preload_length 0
		.amdhsa_user_sgpr_kernarg_preload_offset 0
		.amdhsa_user_sgpr_private_segment_size 0
		.amdhsa_uses_dynamic_stack 0
		.amdhsa_enable_private_segment 0
		.amdhsa_system_sgpr_workgroup_id_x 1
		.amdhsa_system_sgpr_workgroup_id_y 0
		.amdhsa_system_sgpr_workgroup_id_z 0
		.amdhsa_system_sgpr_workgroup_info 0
		.amdhsa_system_vgpr_workitem_id 2
		.amdhsa_next_free_vgpr 251
		.amdhsa_next_free_sgpr 102
		.amdhsa_accum_offset 252
		.amdhsa_reserve_vcc 1
		.amdhsa_float_round_mode_32 0
		.amdhsa_float_round_mode_16_64 0
		.amdhsa_float_denorm_mode_32 3
		.amdhsa_float_denorm_mode_16_64 3
		.amdhsa_dx10_clamp 1
		.amdhsa_ieee_mode 1
		.amdhsa_fp16_overflow 0
		.amdhsa_tg_split 0
		.amdhsa_exception_fp_ieee_invalid_op 0
		.amdhsa_exception_fp_denorm_src 0
		.amdhsa_exception_fp_ieee_div_zero 0
		.amdhsa_exception_fp_ieee_overflow 0
		.amdhsa_exception_fp_ieee_underflow 0
		.amdhsa_exception_fp_ieee_inexact 0
		.amdhsa_exception_int_div_zero 0
	.end_amdhsa_kernel

amdhsa.kernels:
  - .agpr_count:     0
    .args:
      - .offset:         0
        .size:           312
        .value_kind:     by_value
      - .offset:         312
        .size:           4
        .value_kind:     hidden_block_count_x
      - .offset:         316
        .size:           4
        .value_kind:     hidden_block_count_y
      - .offset:         320
        .size:           4
        .value_kind:     hidden_block_count_z
      - .offset:         324
        .size:           2
        .value_kind:     hidden_group_size_x
      - .offset:         326
        .size:           2
        .value_kind:     hidden_group_size_y
      - .offset:         328
        .size:           2
        .value_kind:     hidden_group_size_z
      - .offset:         330
        .size:           2
        .value_kind:     hidden_remainder_x
      - .offset:         332
        .size:           2
        .value_kind:     hidden_remainder_y
      - .offset:         334
        .size:           2
        .value_kind:     hidden_remainder_z
      - .offset:         352
        .size:           8
        .value_kind:     hidden_global_offset_x
      - .offset:         360
        .size:           8
        .value_kind:     hidden_global_offset_y
      - .offset:         368
        .size:           8
        .value_kind:     hidden_global_offset_z
      - .offset:         376
        .size:           2
        .value_kind:     hidden_grid_dims
      - .offset:         400
        .size:           8
        .value_kind:     hidden_multigrid_sync_arg
      - .offset:         432
        .size:           4
        .value_kind:     hidden_dynamic_lds_size
    .group_segment_fixed_size: 0
    .kernarg_segment_align: 8
    .kernarg_segment_size: 568
    .language:       OpenCL C
    .language_version:
      - 2
      - 0
    .max_flat_workgroup_size: 512
    .name:           _Z4mega6Params
    .private_segment_fixed_size: 0
    .sgpr_count:     108
    .sgpr_spill_count: 50
    .symbol:         _Z4mega6Params.kd
    .uniform_work_group_size: 1
    .uses_dynamic_stack: false
    .vgpr_count:     251
    .vgpr_spill_count: 0
    .wavefront_size: 64
